# v011 plus: stick-breaking unit epilogue pairs the two lane halves with v_permlane32_swap and stores four dwordx4 instead of eight dwordx2 per lane
# baseline (speedup 1.0000x reference)
.LBB0_420:
	v_lshlrev_b64 v[34:35], 11, v[130:131]
	v_lshl_add_u64 v[34:35], s[12:13], 0, v[34:35]
	s_lshl_b32 s0, s37, 1
	v_lshl_add_u64 v[34:35], v[34:35], 0, s[0:1]
	v_lshlrev_b32_e32 v0, 1, v133
	v_lshl_add_u64 v[34:35], v[34:35], 0, v[0:1]
	s_mov_b64 s[4:5], 0x30000000
	v_and_b32_e32 v54, 32, v228
	v_lshrrev_b32_e32 v54, 2, v54
	v_mov_b32_e32 v55, 0
	v_lshl_add_u64 v[36:37], v[34:35], 0, s[4:5]
	v_lshl_add_u64 v[36:37], v[36:37], 0, v[54:55]
	v_cvt_pk_bf16_f32 v38, v2, v3
	v_cvt_pk_bf16_f32 v39, v4, v5
	v_cvt_pk_bf16_f32 v40, v6, v7
	v_cvt_pk_bf16_f32 v41, v8, v9
	v_cvt_pk_bf16_f32 v42, v10, v11
	v_cvt_pk_bf16_f32 v43, v12, v13
	v_cvt_pk_bf16_f32 v44, v14, v15
	v_cvt_pk_bf16_f32 v45, v16, v17
	v_cvt_pk_bf16_f32 v46, v18, v19
	v_cvt_pk_bf16_f32 v47, v20, v21
	v_cvt_pk_bf16_f32 v48, v22, v23
	v_cvt_pk_bf16_f32 v49, v24, v25
	v_cvt_pk_bf16_f32 v50, v26, v27
	v_cvt_pk_bf16_f32 v51, v28, v29
	v_cvt_pk_bf16_f32 v52, v30, v31
	v_cvt_pk_bf16_f32 v53, v32, v33
	s_nop 1
	v_permlane32_swap_b32 v38, v40
	v_permlane32_swap_b32 v39, v41
	v_permlane32_swap_b32 v42, v44
	v_permlane32_swap_b32 v43, v45
	v_permlane32_swap_b32 v46, v48
	v_permlane32_swap_b32 v47, v49
	v_permlane32_swap_b32 v50, v52
	v_permlane32_swap_b32 v51, v53
	v_readlane_b32 s4, v253, 8
	flat_store_dwordx4 v[36:37], v[38:41]
	flat_store_dwordx4 v[36:37], v[42:45] offset:32
	s_add_i32 s36, s36, s4
	flat_store_dwordx4 v[36:37], v[46:49] offset:64
	s_cmpk_gt_i32 s36, 0x7ff
	flat_store_dwordx4 v[36:37], v[50:53] offset:96
	s_waitcnt lgkmcnt(0)
	s_barrier
	v_readlane_b32 s5, v253, 9
	s_cbranch_scc1 .LBB0_407
